# P1 q/k rotary epilogue: fq-neighbour lanes exchange halves with v_permlane16_swap so each lane stores 16 contiguous bytes (16 dwordx4 stores per wave instead of 32 dwordx2); also P3b->P3c grid barrier
# speedup vs baseline: 1.0323x; 1.0109x over previous
; __device__ __forceinline__ unsigned cvt_pk_bf16(float lo, float hi) { f32x2_t v = {lo, hi}; bf16x2_t b = __builtin_convertvector(v, bf16x2_t); return __builtin_bit_cast(unsigned, b); }
;     __device__ __forceinline__ void operator()(const f32x4 (&acc)[2][2][4][2], const Unit& u, int wr, int wc, int fr, int fq) const {
;     ...
;             const float sc = (kind == 0) ? qscale : 1.0f;
;             const int j = 4 * (wc & 1) + fq;
;             const int lc0 = (pc0 & ~63) + 4 * j;
; #pragma unroll
;             for (int ai = 0; ai < 2; ++ai)
; #pragma unroll
;                 for (int m = 0; m < 4; ++m) { const int row = row0 + ai * HALF + m * 16; const int pos = row & 4095;
;                     const f32x4 cs = *(const f32x4*)(cosT + pos * 32 + 4 * j) * sc, sn = *(const f32x4*)(sinT + pos * 32 + 4 * j) * sc;
;                     bf16_t* rowp = base + (size_t)row * 512 + lc0;
; #pragma unroll
;                     for (int bj = 0; bj < 2; ++bj) { const f32x4 x1 = acc[ai][bj][m][0], x2 = acc[ai][bj][m][1];
;                         const f32x4 o1 = x1 * cs - x2 * sn, o2 = x2 * cs + x1 * sn;
;                         u32x2 w1, w2; w1.x = cvt_pk_bf16(o1[0], o1[1]); w1.y = cvt_pk_bf16(o1[2], o1[3]); w2.x = cvt_pk_bf16(o2[0], o2[1]); w2.y = cvt_pk_bf16(o2[2], o2[3]);
;                         *(u32x2*)(rowp + bj * HALF) = w1; *(u32x2*)(rowp + bj * HALF + 32) = w2; } }
.LBB0_141:
	s_and_b32 s10, s11, 0x140
	v_or_b32_e32 v146, s10, v157
	v_lshlrev_b32_e32 v188, 1, v146
	v_lshlrev_b32_e32 v159, 7, v144
	v_lshl_add_u64 v[146:147], s[54:55], 0, v[188:189]
	v_bfe_u32 v176, v218, 4, 1
	v_mul_u32_u24_e32 v176, 56, v176
	v_mov_b32_e32 v177, 0
	v_lshl_add_u64 v[146:147], v[176:177], 0, v[146:147]
	v_and_b32_e32 v188, 0x7e780, v159
	v_lshl_add_u64 v[160:161], v[136:137], 0, v[188:189]
	global_load_dwordx4 v[160:163], v[160:161], off
	v_lshlrev_b64 v[168:169], 10, v[144:145]
	v_lshl_add_u64 v[168:169], v[146:147], 0, v[168:169]
	s_waitcnt vmcnt(0)
	v_pk_mul_f32 v[164:165], v[160:161], s[24:25] op_sel_hi:[1,0]
	v_lshl_add_u64 v[160:161], v[138:139], 0, v[188:189]
	v_pk_mul_f32 v[166:167], v[162:163], s[24:25] op_sel_hi:[1,0]
	global_load_dwordx4 v[160:163], v[160:161], off
	s_waitcnt vmcnt(0)
	v_pk_mul_f32 v[162:163], s[24:25], v[162:163] op_sel_hi:[0,1]
	v_pk_mul_f32 v[160:161], s[24:25], v[160:161] op_sel_hi:[0,1]
	v_pk_mul_f32 v[170:171], v[120:121], v[160:161]
	v_pk_mul_f32 v[172:173], v[122:123], v[162:163]
	v_pk_mul_f32 v[120:121], v[120:121], v[164:165]
	v_pk_mul_f32 v[122:123], v[122:123], v[166:167]
	v_pk_fma_f32 v[172:173], v[126:127], v[166:167], v[172:173] neg_lo:[0,0,1] neg_hi:[0,0,1]
	v_pk_fma_f32 v[170:171], v[124:125], v[164:165], v[170:171] neg_lo:[0,0,1] neg_hi:[0,0,1]
	v_pk_fma_f32 v[122:123], v[126:127], v[162:163], v[122:123]
	v_pk_fma_f32 v[120:121], v[124:125], v[160:161], v[120:121]
	v_cvt_pk_bf16_f32 v180, v170, v171
	v_cvt_pk_bf16_f32 v181, v172, v173
	v_cvt_pk_bf16_f32 v182, v120, v121
	v_cvt_pk_bf16_f32 v183, v122, v123
	s_nop 1
	v_permlane16_swap_b32_e32 v180, v182
	v_permlane16_swap_b32_e32 v181, v183
	global_store_dwordx4 v[168:169], v[180:183], off
	v_pk_mul_f32 v[120:121], v[112:113], v[160:161]
	v_pk_mul_f32 v[122:123], v[114:115], v[162:163]
	v_pk_mul_f32 v[112:113], v[112:113], v[164:165]
	v_pk_fma_f32 v[122:123], v[118:119], v[166:167], v[122:123] neg_lo:[0,0,1] neg_hi:[0,0,1]
	v_pk_fma_f32 v[120:121], v[116:117], v[164:165], v[120:121] neg_lo:[0,0,1] neg_hi:[0,0,1]
	v_pk_mul_f32 v[114:115], v[114:115], v[166:167]
	v_pk_fma_f32 v[112:113], v[116:117], v[160:161], v[112:113]
	v_pk_fma_f32 v[114:115], v[118:119], v[162:163], v[114:115]
	v_cvt_pk_bf16_f32 v198, v120, v121
	v_cvt_pk_bf16_f32 v199, v122, v123
	v_cvt_pk_bf16_f32 v200, v112, v113
	v_cvt_pk_bf16_f32 v201, v114, v115
	s_nop 1
	v_permlane16_swap_b32_e32 v198, v200
	v_permlane16_swap_b32_e32 v199, v201
	global_store_dwordx4 v[168:169], v[198:201], off offset:256
	v_lshlrev_b32_e32 v112, 7, v152
	v_and_b32_e32 v188, 0x7ef80, v112
	v_lshl_add_u64 v[112:113], v[136:137], 0, v[188:189]
	global_load_dwordx4 v[112:115], v[112:113], off
	v_lshlrev_b64 v[120:121], 10, v[152:153]
	v_lshl_add_u64 v[120:121], v[146:147], 0, v[120:121]
	s_waitcnt vmcnt(0)
	v_pk_mul_f32 v[116:117], s[24:25], v[112:113] op_sel_hi:[0,1]
	v_lshl_add_u64 v[112:113], v[138:139], 0, v[188:189]
	v_pk_mul_f32 v[118:119], s[24:25], v[114:115] op_sel_hi:[0,1]
	global_load_dwordx4 v[112:115], v[112:113], off
	s_waitcnt vmcnt(0)
	v_pk_mul_f32 v[114:115], s[24:25], v[114:115] op_sel_hi:[0,1]
	v_pk_mul_f32 v[112:113], s[24:25], v[112:113] op_sel_hi:[0,1]
	v_pk_mul_f32 v[122:123], v[104:105], v[112:113]
	v_pk_mul_f32 v[124:125], v[106:107], v[114:115]
	v_pk_fma_f32 v[122:123], v[108:109], v[116:117], v[122:123] neg_lo:[0,0,1] neg_hi:[0,0,1]
	v_pk_fma_f32 v[124:125], v[110:111], v[118:119], v[124:125] neg_lo:[0,0,1] neg_hi:[0,0,1]
	v_pk_mul_f32 v[108:109], v[108:109], v[112:113]
	v_pk_mul_f32 v[110:111], v[110:111], v[114:115]
	v_pk_fma_f32 v[104:105], v[104:105], v[116:117], v[108:109]
	v_pk_fma_f32 v[106:107], v[106:107], v[118:119], v[110:111]
	v_cvt_pk_bf16_f32 v180, v122, v123
	v_cvt_pk_bf16_f32 v181, v124, v125
	v_cvt_pk_bf16_f32 v182, v104, v105
	v_cvt_pk_bf16_f32 v183, v106, v107
	s_nop 1
	v_permlane16_swap_b32_e32 v180, v182
	v_permlane16_swap_b32_e32 v181, v183
	global_store_dwordx4 v[120:121], v[180:183], off
	v_pk_mul_f32 v[104:105], v[96:97], v[112:113]
	v_pk_mul_f32 v[106:107], v[98:99], v[114:115]
	v_pk_fma_f32 v[104:105], v[100:101], v[116:117], v[104:105] neg_lo:[0,0,1] neg_hi:[0,0,1]
	v_pk_mul_f32 v[100:101], v[100:101], v[112:113]
	v_pk_fma_f32 v[106:107], v[102:103], v[118:119], v[106:107] neg_lo:[0,0,1] neg_hi:[0,0,1]
	v_pk_mul_f32 v[102:103], v[102:103], v[114:115]
	v_pk_fma_f32 v[96:97], v[96:97], v[116:117], v[100:101]
	v_pk_fma_f32 v[98:99], v[98:99], v[118:119], v[102:103]
	v_cvt_pk_bf16_f32 v198, v104, v105
	v_cvt_pk_bf16_f32 v199, v106, v107
	v_cvt_pk_bf16_f32 v200, v96, v97
	v_cvt_pk_bf16_f32 v201, v98, v99
	s_nop 1
	v_permlane16_swap_b32_e32 v198, v200
	v_permlane16_swap_b32_e32 v199, v201
	global_store_dwordx4 v[120:121], v[198:201], off offset:256
	v_lshlrev_b32_e32 v96, 7, v150
	v_and_b32_e32 v188, 0x7f780, v96
	v_lshl_add_u64 v[96:97], v[136:137], 0, v[188:189]
	global_load_dwordx4 v[96:99], v[96:97], off
	v_lshlrev_b64 v[104:105], 10, v[150:151]
	v_lshl_add_u64 v[104:105], v[146:147], 0, v[104:105]
	s_waitcnt vmcnt(0)
	v_pk_mul_f32 v[100:101], s[24:25], v[96:97] op_sel_hi:[0,1]
	v_lshl_add_u64 v[96:97], v[138:139], 0, v[188:189]
	v_pk_mul_f32 v[102:103], s[24:25], v[98:99] op_sel_hi:[0,1]
	global_load_dwordx4 v[96:99], v[96:97], off
	s_waitcnt vmcnt(0)
; __device__ __forceinline__ unsigned cvt_pk_bf16(float lo, float hi) { f32x2_t v = {lo, hi}; bf16x2_t b = __builtin_convertvector(v, bf16x2_t); return __builtin_bit_cast(unsigned, b); }
;     __device__ __forceinline__ void operator()(const f32x4 (&acc)[2][2][4][2], const Unit& u, int wr, int wc, int fr, int fq) const {
;     ...
;                 for (int m = 0; m < 4; ++m) { const int row = row0 + ai * HALF + m * 16; const int pos = row & 4095;
;                     const f32x4 cs = *(const f32x4*)(cosT + pos * 32 + 4 * j) * sc, sn = *(const f32x4*)(sinT + pos * 32 + 4 * j) * sc;
;                     bf16_t* rowp = base + (size_t)row * 512 + lc0;
; #pragma unroll
;                     for (int bj = 0; bj < 2; ++bj) { const f32x4 x1 = acc[ai][bj][m][0], x2 = acc[ai][bj][m][1];
;                         const f32x4 o1 = x1 * cs - x2 * sn, o2 = x2 * cs + x1 * sn;
;                         u32x2 w1, w2; w1.x = cvt_pk_bf16(o1[0], o1[1]); w1.y = cvt_pk_bf16(o1[2], o1[3]); w2.x = cvt_pk_bf16(o2[0], o2[1]); w2.y = cvt_pk_bf16(o2[2], o2[3]);
;                         *(u32x2*)(rowp + bj * HALF) = w1; *(u32x2*)(rowp + bj * HALF + 32) = w2; } }
	v_pk_mul_f32 v[98:99], s[24:25], v[98:99] op_sel_hi:[0,1]
	v_pk_mul_f32 v[96:97], s[24:25], v[96:97] op_sel_hi:[0,1]
	v_pk_mul_f32 v[106:107], v[88:89], v[96:97]
	v_pk_mul_f32 v[108:109], v[90:91], v[98:99]
	v_pk_fma_f32 v[106:107], v[92:93], v[100:101], v[106:107] neg_lo:[0,0,1] neg_hi:[0,0,1]
	v_pk_fma_f32 v[108:109], v[94:95], v[102:103], v[108:109] neg_lo:[0,0,1] neg_hi:[0,0,1]
	v_pk_mul_f32 v[92:93], v[92:93], v[96:97]
	v_pk_mul_f32 v[94:95], v[94:95], v[98:99]
	v_pk_fma_f32 v[88:89], v[88:89], v[100:101], v[92:93]
	v_pk_fma_f32 v[90:91], v[90:91], v[102:103], v[94:95]
	v_cvt_pk_bf16_f32 v180, v106, v107
	v_cvt_pk_bf16_f32 v181, v108, v109
	v_cvt_pk_bf16_f32 v182, v88, v89
	v_cvt_pk_bf16_f32 v183, v90, v91
	s_nop 1
	v_permlane16_swap_b32_e32 v180, v182
	v_permlane16_swap_b32_e32 v181, v183
	global_store_dwordx4 v[104:105], v[180:183], off
	v_pk_mul_f32 v[88:89], v[80:81], v[96:97]
	v_pk_mul_f32 v[90:91], v[82:83], v[98:99]
	v_pk_fma_f32 v[88:89], v[84:85], v[100:101], v[88:89] neg_lo:[0,0,1] neg_hi:[0,0,1]
	v_pk_mul_f32 v[84:85], v[84:85], v[96:97]
	v_pk_fma_f32 v[90:91], v[86:87], v[102:103], v[90:91] neg_lo:[0,0,1] neg_hi:[0,0,1]
	v_pk_mul_f32 v[86:87], v[86:87], v[98:99]
	v_pk_fma_f32 v[80:81], v[80:81], v[100:101], v[84:85]
	v_pk_fma_f32 v[82:83], v[82:83], v[102:103], v[86:87]
	v_cvt_pk_bf16_f32 v198, v88, v89
	v_cvt_pk_bf16_f32 v199, v90, v91
	v_cvt_pk_bf16_f32 v200, v80, v81
	v_cvt_pk_bf16_f32 v201, v82, v83
	s_nop 1
	v_permlane16_swap_b32_e32 v198, v200
	v_permlane16_swap_b32_e32 v199, v201
	global_store_dwordx4 v[104:105], v[198:201], off offset:256
	v_lshlrev_b32_e32 v80, 7, v148
	v_and_b32_e32 v188, 0x7ff80, v80
	v_lshl_add_u64 v[80:81], v[136:137], 0, v[188:189]
	global_load_dwordx4 v[80:83], v[80:81], off
	v_lshlrev_b64 v[88:89], 10, v[148:149]
	v_lshl_add_u64 v[88:89], v[146:147], 0, v[88:89]
	s_waitcnt vmcnt(0)
	v_pk_mul_f32 v[84:85], s[24:25], v[80:81] op_sel_hi:[0,1]
	v_lshl_add_u64 v[80:81], v[138:139], 0, v[188:189]
	v_pk_mul_f32 v[86:87], s[24:25], v[82:83] op_sel_hi:[0,1]
	global_load_dwordx4 v[80:83], v[80:81], off
	s_waitcnt vmcnt(0)
	v_pk_mul_f32 v[82:83], s[24:25], v[82:83] op_sel_hi:[0,1]
	v_pk_mul_f32 v[80:81], s[24:25], v[80:81] op_sel_hi:[0,1]
	v_pk_mul_f32 v[90:91], v[72:73], v[80:81]
	v_pk_mul_f32 v[92:93], v[74:75], v[82:83]
	v_pk_fma_f32 v[90:91], v[76:77], v[84:85], v[90:91] neg_lo:[0,0,1] neg_hi:[0,0,1]
	v_pk_fma_f32 v[92:93], v[78:79], v[86:87], v[92:93] neg_lo:[0,0,1] neg_hi:[0,0,1]
	v_pk_mul_f32 v[76:77], v[76:77], v[80:81]
	v_pk_mul_f32 v[78:79], v[78:79], v[82:83]
	v_pk_fma_f32 v[72:73], v[72:73], v[84:85], v[76:77]
	v_pk_fma_f32 v[74:75], v[74:75], v[86:87], v[78:79]
	v_cvt_pk_bf16_f32 v180, v90, v91
	v_cvt_pk_bf16_f32 v181, v92, v93
	v_cvt_pk_bf16_f32 v182, v72, v73
	v_cvt_pk_bf16_f32 v183, v74, v75
	s_nop 1
	v_permlane16_swap_b32_e32 v180, v182
	v_permlane16_swap_b32_e32 v181, v183
	global_store_dwordx4 v[88:89], v[180:183], off
	v_pk_mul_f32 v[72:73], v[64:65], v[80:81]
	v_pk_mul_f32 v[74:75], v[66:67], v[82:83]
	v_pk_fma_f32 v[72:73], v[68:69], v[84:85], v[72:73] neg_lo:[0,0,1] neg_hi:[0,0,1]
	v_pk_fma_f32 v[74:75], v[70:71], v[86:87], v[74:75] neg_lo:[0,0,1] neg_hi:[0,0,1]
	v_pk_mul_f32 v[68:69], v[68:69], v[80:81]
	v_pk_mul_f32 v[70:71], v[70:71], v[82:83]
	v_pk_fma_f32 v[64:65], v[64:65], v[84:85], v[68:69]
	v_pk_fma_f32 v[66:67], v[66:67], v[86:87], v[70:71]
	v_cvt_pk_bf16_f32 v198, v72, v73
	v_cvt_pk_bf16_f32 v199, v74, v75
	v_cvt_pk_bf16_f32 v200, v64, v65
	v_cvt_pk_bf16_f32 v201, v66, v67
	s_nop 1
	v_permlane16_swap_b32_e32 v198, v200
	v_permlane16_swap_b32_e32 v199, v201
	global_store_dwordx4 v[88:89], v[198:201], off offset:256
	v_add_u32_e32 v68, 0x80, v144
	v_lshlrev_b32_e32 v64, 7, v68
	v_and_b32_e32 v188, 0x7e780, v64
	v_lshl_add_u64 v[64:65], v[136:137], 0, v[188:189]
	global_load_dwordx4 v[64:67], v[64:65], off
	v_ashrrev_i32_e32 v69, 31, v68
	v_lshlrev_b64 v[68:69], 10, v[68:69]
	v_lshl_add_u64 v[68:69], v[146:147], 0, v[68:69]
	s_waitcnt vmcnt(0)
	v_pk_mul_f32 v[70:71], s[24:25], v[64:65] op_sel_hi:[0,1]
	v_lshl_add_u64 v[64:65], v[138:139], 0, v[188:189]
	v_pk_mul_f32 v[72:73], s[24:25], v[66:67] op_sel_hi:[0,1]
	global_load_dwordx4 v[64:67], v[64:65], off
	s_waitcnt vmcnt(0)
	v_pk_mul_f32 v[66:67], s[24:25], v[66:67] op_sel_hi:[0,1]
	v_pk_mul_f32 v[64:65], s[24:25], v[64:65] op_sel_hi:[0,1]
	v_pk_mul_f32 v[74:75], v[56:57], v[64:65]
	v_pk_mul_f32 v[76:77], v[58:59], v[66:67]
	v_pk_fma_f32 v[74:75], v[60:61], v[70:71], v[74:75] neg_lo:[0,0,1] neg_hi:[0,0,1]
	v_pk_fma_f32 v[76:77], v[62:63], v[72:73], v[76:77] neg_lo:[0,0,1] neg_hi:[0,0,1]
	v_pk_mul_f32 v[60:61], v[60:61], v[64:65]
	v_pk_mul_f32 v[62:63], v[62:63], v[66:67]
	v_pk_fma_f32 v[56:57], v[56:57], v[70:71], v[60:61]
	v_pk_fma_f32 v[58:59], v[58:59], v[72:73], v[62:63]
	v_cvt_pk_bf16_f32 v180, v74, v75
	v_cvt_pk_bf16_f32 v181, v76, v77
	v_cvt_pk_bf16_f32 v182, v56, v57
	v_cvt_pk_bf16_f32 v183, v58, v59
	s_nop 1
	v_permlane16_swap_b32_e32 v180, v182
	v_permlane16_swap_b32_e32 v181, v183
	global_store_dwordx4 v[68:69], v[180:183], off
	v_pk_mul_f32 v[56:57], v[48:49], v[64:65]
	v_pk_mul_f32 v[58:59], v[50:51], v[66:67]
	v_pk_fma_f32 v[56:57], v[52:53], v[70:71], v[56:57] neg_lo:[0,0,1] neg_hi:[0,0,1]
	v_pk_fma_f32 v[58:59], v[54:55], v[72:73], v[58:59] neg_lo:[0,0,1] neg_hi:[0,0,1]
	v_pk_mul_f32 v[52:53], v[52:53], v[64:65]
	v_pk_mul_f32 v[54:55], v[54:55], v[66:67]
	v_pk_fma_f32 v[48:49], v[48:49], v[70:71], v[52:53]
	v_pk_fma_f32 v[50:51], v[50:51], v[72:73], v[54:55]
	v_cvt_pk_bf16_f32 v198, v56, v57
	v_cvt_pk_bf16_f32 v199, v58, v59
	v_cvt_pk_bf16_f32 v200, v48, v49
	v_cvt_pk_bf16_f32 v201, v50, v51
	s_nop 1
	v_permlane16_swap_b32_e32 v198, v200
	v_permlane16_swap_b32_e32 v199, v201
	global_store_dwordx4 v[68:69], v[198:201], off offset:256
	v_add_u32_e32 v52, 0x90, v144
	v_lshlrev_b32_e32 v48, 7, v52
	v_and_b32_e32 v188, 0x7ef80, v48
	v_lshl_add_u64 v[48:49], v[136:137], 0, v[188:189]
	global_load_dwordx4 v[48:51], v[48:49], off
	v_ashrrev_i32_e32 v53, 31, v52
	v_lshlrev_b64 v[52:53], 10, v[52:53]
	v_lshl_add_u64 v[52:53], v[146:147], 0, v[52:53]
	s_waitcnt vmcnt(0)
; __device__ __forceinline__ unsigned cvt_pk_bf16(float lo, float hi) { f32x2_t v = {lo, hi}; bf16x2_t b = __builtin_convertvector(v, bf16x2_t); return __builtin_bit_cast(unsigned, b); }
;     __device__ __forceinline__ void operator()(const f32x4 (&acc)[2][2][4][2], const Unit& u, int wr, int wc, int fr, int fq) const {
;     ...
;                 for (int m = 0; m < 4; ++m) { const int row = row0 + ai * HALF + m * 16; const int pos = row & 4095;
;                     const f32x4 cs = *(const f32x4*)(cosT + pos * 32 + 4 * j) * sc, sn = *(const f32x4*)(sinT + pos * 32 + 4 * j) * sc;
;                     bf16_t* rowp = base + (size_t)row * 512 + lc0;
; #pragma unroll
;                     for (int bj = 0; bj < 2; ++bj) { const f32x4 x1 = acc[ai][bj][m][0], x2 = acc[ai][bj][m][1];
;                         const f32x4 o1 = x1 * cs - x2 * sn, o2 = x2 * cs + x1 * sn;
;                         u32x2 w1, w2; w1.x = cvt_pk_bf16(o1[0], o1[1]); w1.y = cvt_pk_bf16(o1[2], o1[3]); w2.x = cvt_pk_bf16(o2[0], o2[1]); w2.y = cvt_pk_bf16(o2[2], o2[3]);
;                         *(u32x2*)(rowp + bj * HALF) = w1; *(u32x2*)(rowp + bj * HALF + 32) = w2; } }
	v_pk_mul_f32 v[54:55], s[24:25], v[48:49] op_sel_hi:[0,1]
	v_lshl_add_u64 v[48:49], v[138:139], 0, v[188:189]
	v_pk_mul_f32 v[56:57], s[24:25], v[50:51] op_sel_hi:[0,1]
	global_load_dwordx4 v[48:51], v[48:49], off
	s_waitcnt vmcnt(0)
	v_pk_mul_f32 v[50:51], s[24:25], v[50:51] op_sel_hi:[0,1]
	v_pk_mul_f32 v[48:49], s[24:25], v[48:49] op_sel_hi:[0,1]
	v_pk_mul_f32 v[58:59], v[40:41], v[48:49]
	v_pk_mul_f32 v[60:61], v[42:43], v[50:51]
	v_pk_fma_f32 v[58:59], v[44:45], v[54:55], v[58:59] neg_lo:[0,0,1] neg_hi:[0,0,1]
	v_pk_fma_f32 v[60:61], v[46:47], v[56:57], v[60:61] neg_lo:[0,0,1] neg_hi:[0,0,1]
	v_pk_mul_f32 v[44:45], v[44:45], v[48:49]
	v_pk_mul_f32 v[46:47], v[46:47], v[50:51]
	v_pk_fma_f32 v[40:41], v[40:41], v[54:55], v[44:45]
	v_pk_fma_f32 v[42:43], v[42:43], v[56:57], v[46:47]
	v_cvt_pk_bf16_f32 v180, v58, v59
	v_cvt_pk_bf16_f32 v181, v60, v61
	v_cvt_pk_bf16_f32 v182, v40, v41
	v_cvt_pk_bf16_f32 v183, v42, v43
	s_nop 1
	v_permlane16_swap_b32_e32 v180, v182
	v_permlane16_swap_b32_e32 v181, v183
	global_store_dwordx4 v[52:53], v[180:183], off
	v_pk_mul_f32 v[40:41], v[32:33], v[48:49]
	v_pk_mul_f32 v[42:43], v[34:35], v[50:51]
	v_pk_fma_f32 v[40:41], v[36:37], v[54:55], v[40:41] neg_lo:[0,0,1] neg_hi:[0,0,1]
	v_pk_fma_f32 v[42:43], v[38:39], v[56:57], v[42:43] neg_lo:[0,0,1] neg_hi:[0,0,1]
	v_pk_mul_f32 v[36:37], v[36:37], v[48:49]
	v_pk_mul_f32 v[38:39], v[38:39], v[50:51]
	v_pk_fma_f32 v[32:33], v[32:33], v[54:55], v[36:37]
	v_pk_fma_f32 v[34:35], v[34:35], v[56:57], v[38:39]
	v_cvt_pk_bf16_f32 v198, v40, v41
	v_cvt_pk_bf16_f32 v199, v42, v43
	v_cvt_pk_bf16_f32 v200, v32, v33
	v_cvt_pk_bf16_f32 v201, v34, v35
	s_nop 1
	v_permlane16_swap_b32_e32 v198, v200
	v_permlane16_swap_b32_e32 v199, v201
	global_store_dwordx4 v[52:53], v[198:201], off offset:256
	v_add_u32_e32 v36, 0xa0, v144
	v_lshlrev_b32_e32 v32, 7, v36
	v_and_b32_e32 v188, 0x7f780, v32
	v_lshl_add_u64 v[32:33], v[136:137], 0, v[188:189]
	global_load_dwordx4 v[32:35], v[32:33], off
	v_ashrrev_i32_e32 v37, 31, v36
	v_lshlrev_b64 v[36:37], 10, v[36:37]
	v_lshl_add_u64 v[36:37], v[146:147], 0, v[36:37]
	s_waitcnt vmcnt(0)
	v_pk_mul_f32 v[38:39], s[24:25], v[32:33] op_sel_hi:[0,1]
	v_lshl_add_u64 v[32:33], v[138:139], 0, v[188:189]
	v_pk_mul_f32 v[40:41], s[24:25], v[34:35] op_sel_hi:[0,1]
	global_load_dwordx4 v[32:35], v[32:33], off
	s_waitcnt vmcnt(0)
	v_pk_mul_f32 v[34:35], s[24:25], v[34:35] op_sel_hi:[0,1]
	v_pk_mul_f32 v[32:33], s[24:25], v[32:33] op_sel_hi:[0,1]
	v_pk_mul_f32 v[42:43], v[24:25], v[32:33]
	v_pk_mul_f32 v[44:45], v[26:27], v[34:35]
	v_pk_fma_f32 v[42:43], v[28:29], v[38:39], v[42:43] neg_lo:[0,0,1] neg_hi:[0,0,1]
	v_pk_fma_f32 v[44:45], v[30:31], v[40:41], v[44:45] neg_lo:[0,0,1] neg_hi:[0,0,1]
	v_pk_mul_f32 v[28:29], v[28:29], v[32:33]
	v_pk_mul_f32 v[30:31], v[30:31], v[34:35]
	v_pk_fma_f32 v[24:25], v[24:25], v[38:39], v[28:29]
	v_pk_fma_f32 v[26:27], v[26:27], v[40:41], v[30:31]
	v_cvt_pk_bf16_f32 v180, v42, v43
	v_cvt_pk_bf16_f32 v181, v44, v45
	v_cvt_pk_bf16_f32 v182, v24, v25
	v_cvt_pk_bf16_f32 v183, v26, v27
	s_nop 1
	v_permlane16_swap_b32_e32 v180, v182
	v_permlane16_swap_b32_e32 v181, v183
	global_store_dwordx4 v[36:37], v[180:183], off
	v_pk_mul_f32 v[24:25], v[16:17], v[32:33]
	v_pk_mul_f32 v[26:27], v[18:19], v[34:35]
	v_pk_fma_f32 v[24:25], v[20:21], v[38:39], v[24:25] neg_lo:[0,0,1] neg_hi:[0,0,1]
	v_pk_fma_f32 v[26:27], v[22:23], v[40:41], v[26:27] neg_lo:[0,0,1] neg_hi:[0,0,1]
	v_pk_mul_f32 v[20:21], v[20:21], v[32:33]
	v_pk_mul_f32 v[22:23], v[22:23], v[34:35]
	v_pk_fma_f32 v[16:17], v[16:17], v[38:39], v[20:21]
	v_pk_fma_f32 v[18:19], v[18:19], v[40:41], v[22:23]
	v_cvt_pk_bf16_f32 v198, v24, v25
	v_cvt_pk_bf16_f32 v199, v26, v27
	v_cvt_pk_bf16_f32 v200, v16, v17
	v_cvt_pk_bf16_f32 v201, v18, v19
	s_nop 1
	v_permlane16_swap_b32_e32 v198, v200
	v_permlane16_swap_b32_e32 v199, v201
	global_store_dwordx4 v[36:37], v[198:201], off offset:256
	v_add_u32_e32 v20, 0xb0, v144
	v_lshlrev_b32_e32 v16, 7, v20
	v_and_b32_e32 v188, 0x7ff80, v16
	v_lshl_add_u64 v[16:17], v[136:137], 0, v[188:189]
	global_load_dwordx4 v[16:19], v[16:17], off
	v_ashrrev_i32_e32 v21, 31, v20
	v_lshlrev_b64 v[20:21], 10, v[20:21]
	v_lshl_add_u64 v[20:21], v[146:147], 0, v[20:21]
	s_waitcnt vmcnt(0)
	v_pk_mul_f32 v[22:23], s[24:25], v[16:17] op_sel_hi:[0,1]
	v_lshl_add_u64 v[16:17], v[138:139], 0, v[188:189]
	v_pk_mul_f32 v[24:25], s[24:25], v[18:19] op_sel_hi:[0,1]
	global_load_dwordx4 v[16:19], v[16:17], off
	s_waitcnt vmcnt(0)
	v_pk_mul_f32 v[18:19], s[24:25], v[18:19] op_sel_hi:[0,1]
	v_pk_mul_f32 v[16:17], s[24:25], v[16:17] op_sel_hi:[0,1]
	v_pk_mul_f32 v[26:27], v[8:9], v[16:17]
	v_pk_mul_f32 v[28:29], v[10:11], v[18:19]
	v_pk_fma_f32 v[26:27], v[12:13], v[22:23], v[26:27] neg_lo:[0,0,1] neg_hi:[0,0,1]
	v_pk_fma_f32 v[28:29], v[14:15], v[24:25], v[28:29] neg_lo:[0,0,1] neg_hi:[0,0,1]
	v_pk_mul_f32 v[12:13], v[12:13], v[16:17]
	v_pk_mul_f32 v[14:15], v[14:15], v[18:19]
	v_pk_fma_f32 v[8:9], v[8:9], v[22:23], v[12:13]
	v_pk_fma_f32 v[10:11], v[10:11], v[24:25], v[14:15]
	v_cvt_pk_bf16_f32 v180, v26, v27
	v_cvt_pk_bf16_f32 v181, v28, v29
	v_cvt_pk_bf16_f32 v182, v8, v9
	v_cvt_pk_bf16_f32 v183, v10, v11
	s_nop 1
	v_permlane16_swap_b32_e32 v180, v182
	v_permlane16_swap_b32_e32 v181, v183
	global_store_dwordx4 v[20:21], v[180:183], off
	v_pk_mul_f32 v[8:9], v[0:1], v[16:17]
	v_pk_mul_f32 v[10:11], v[2:3], v[18:19]
	v_pk_fma_f32 v[8:9], v[4:5], v[22:23], v[8:9] neg_lo:[0,0,1] neg_hi:[0,0,1]
	v_pk_fma_f32 v[10:11], v[6:7], v[24:25], v[10:11] neg_lo:[0,0,1] neg_hi:[0,0,1]
	v_pk_mul_f32 v[4:5], v[4:5], v[16:17]
	v_pk_mul_f32 v[6:7], v[6:7], v[18:19]
	v_pk_fma_f32 v[0:1], v[0:1], v[22:23], v[4:5]
	v_pk_fma_f32 v[2:3], v[2:3], v[24:25], v[6:7]
	v_cvt_pk_bf16_f32 v198, v8, v9
	v_cvt_pk_bf16_f32 v199, v10, v11
	v_cvt_pk_bf16_f32 v200, v0, v1
	v_cvt_pk_bf16_f32 v201, v2, v3
	s_nop 1
	v_permlane16_swap_b32_e32 v198, v200
	v_permlane16_swap_b32_e32 v199, v201
	global_store_dwordx4 v[20:21], v[198:201], off offset:256
	s_andn2_b64 vcc, exec, s[38:39]
	s_mov_b64 s[38:39], -1
	s_cbranch_vccnz .LBB0_128

; template <class Epi, class Sched, bool ALIGN_EPI = false, bool SP2 = false>
; __device__ __forceinline__ void gemm_phase(PG8_LAS unsigned char* lds, const Gemm g, const Sched& S, const Epi& E) {
;     ...
;     const int tid = tid_, wid = __builtin_amdgcn_readfirstlane(tid >> 6), lane = tid & 63, wr = wid >> 2, wc = wid & 3, fr = lane & 15, fq = lane >> 4;
;     const int K = g.K, nt = K / BK;
;     unsigned voffA[2], voffB[2];
; #pragma unroll
;     for (int i = 0; i < 2; ++i) { int R, C; stage_rc(tid * 16 + i * 8192, R, C); const int Rb = Epi::PERM ? ((R & ~31) + perm32(R & 31)) : R;
;         voffA[i] = (unsigned)(R * K + C) * 2u; voffB[i] = (unsigned)(Rb * K + C) * 2u; }
;     const size_t kstep = (size_t)(BK * 2);
;     const size_t hstep = (size_t)HALF * K * 2;
;     const size_t tstep = 2 * hstep;
;     const unsigned ldsw = (unsigned)wid * 1024u;
;     const int aoff = lds_byte(wr * 64 + fr, fq * 8), boff = lds_byte(wc * 32 + fr, fq * 8);
;     ...
;     Unit cur, nxt; int ui = 0;
;     if (!S.next(0, cur)) return;
;     f32x4 acc[2][2][4][2];
; #pragma unroll
;     for (int a = 0; a < 2; ++a)
; #pragma unroll
;         for (int b = 0; b < 2; ++b)
; #pragma unroll
;             for (int m = 0; m < 4; ++m)
; #pragma unroll
;                 for (int n = 0; n < 2; ++n) acc[a][b][m][n] = (f32x4){0.f, 0.f, 0.f, 0.f};
;     bf16x8 At[4][2], B0[2][2], B1[2][2];
;     const char* cA = (const char*)g.A + (size_t)cur.pm * tstep; const char* cB = (const char*)g.Bt + (size_t)cur.pn * tstep;
;     S.a_ready(cur);
;     if constexpr (SP2) {
;         PG8_STAGE(PG8_SB(0, 0), cB, voffB); PG8_STAGE(PG8_SB(0, 1), cB + hstep, voffB); PG8_STAGE(PG8_SA(0, 0), cA, voffA); PG8_STAGE(PG8_SA(0, 1), cA + hstep, voffA);
;         if (wr == 1) PG8_BAR;
;         PG8_WAIT_V(2); PG8_BAR;
;         PG8_STAGE(PG8_SB(1, 0), cB + kstep, voffB); PG8_STAGE(PG8_SA(1, 0), cA + kstep, voffA); PG8_STAGE(PG8_SB(1, 1), cB + hstep + kstep, voffB);
;         PG8_WAIT_V(6); PG8_BAR;
;     } else {
;         PG8_STAGE(PG8_SB(0, 0), cB, voffB); PG8_STAGE(PG8_SA(0, 0), cA, voffA); PG8_STAGE(PG8_SB(0, 1), cB + hstep, voffB); PG8_STAGE(PG8_SA(0, 1), cA + hstep, voffA);
;         if (wr == 1) PG8_BAR;
;         PG8_WAIT_V(4); PG8_BAR;
;         PG8_STAGE(PG8_SB(1, 0), cB + kstep, voffB); PG8_STAGE(PG8_SA(1, 0), cA + kstep, voffA); PG8_STAGE(PG8_SB(1, 1), cB + hstep + kstep, voffB);
.LBB0_513:
	s_waitcnt vmcnt(0)
	s_barrier
	s_mov_b64 s[16:17], exec
.LBB0_561:
	s_or_b64 exec, exec, s[16:17]
	v_readlane_b32 s8, v255, 35
	v_mov_b32_e32 v14, v218
	v_readlane_b32 s9, v255, 36
	s_waitcnt lgkmcnt(0)
	s_barrier
	s_mov_b32 s0, 0
	s_and_b64 vcc, exec, s[8:9]
	v_readfirstlane_b32 s10, v14
	s_cbranch_vccnz .LBB0_581
	v_lshlrev_b32_e32 v0, 4, v14
	v_add_u32_e32 v1, 0x2000, v0
	v_ashrrev_i32_e32 v2, 31, v1
	v_lshrrev_b32_e32 v2, 22, v2
	v_add_u32_e32 v2, v1, v2
	v_ashrrev_i32_e32 v8, 10, v2
	v_mul_i32_i24_e32 v2, 0x400, v8
	v_sub_u32_e32 v1, v1, v2
	v_lshrrev_b32_e32 v2, 4, v1
	v_bitop3_b32 v1, v2, v1, 32 bitop3:0x6c
	v_ashrrev_i32_e32 v2, 31, v1
	v_lshrrev_b32_e32 v2, 26, v2
	v_add_u32_e32 v2, v1, v2
	v_lshlrev_b32_e32 v3, 3, v8
	v_ashrrev_i32_e32 v9, 6, v2
	v_and_b32_e32 v3, -16, v3
	v_add_u32_e32 v3, v9, v3
	v_and_b32_e32 v4, 3, v9
	s_mov_b32 s12, 0x3fffe0
	v_lshrrev_b32_e32 v5, 2, v3
	v_lshlrev_b32_e32 v6, 1, v3
	v_and_b32_e32 v2, 0xc0, v2
	v_and_or_b32 v4, v3, s12, v4
	v_and_b32_e32 v5, 4, v5
	v_and_b32_e32 v6, 24, v6
	v_sub_u32_e32 v1, v1, v2
	v_or3_b32 v4, v4, v5, v6
	v_lshlrev_b32_e32 v5, 5, v8
	v_ashrrev_i16_sdwa v1, v220, sext(v1) dst_sel:DWORD dst_unused:UNUSED_PAD src0_sel:DWORD src1_sel:BYTE_0
	v_and_b32_e32 v5, 32, v5
	v_bfe_i32 v10, v1, 0, 16
	v_add_lshl_u32 v1, v5, v10, 1
	v_lshl_add_u32 v198, v4, 10, v1
	v_lshl_add_u32 v200, v3, 10, v1
	v_bfe_i32 v1, v14, 27, 1
	v_lshrrev_b32_e32 v1, 22, v1
	s_ashr_i32 s1, s0, 31
	v_readlane_b32 s8, v254, 0
	v_add_u32_e32 v1, v0, v1
	v_readlane_b32 s9, v254, 1
	s_add_u32 s0, s8, s0
	v_and_b32_e32 v1, 0xfffffc00, v1
	s_addc_u32 s1, s9, s1
	v_sub_u32_e32 v0, v0, v1
	s_load_dwordx2 s[40:41], s[0:1], 0x70
	v_lshrrev_b32_e32 v1, 4, v0
	v_ashrrev_i32_e32 v2, 31, v14
	v_bitop3_b32 v0, v1, v0, 32 bitop3:0x6c
	v_lshrrev_b32_e32 v2, 26, v2
	v_ashrrev_i32_e32 v1, 31, v0
	v_add_u32_e32 v2, v14, v2
	v_lshrrev_b32_e32 v1, 26, v1
	v_ashrrev_i32_e32 v12, 6, v2
	v_add_u32_e32 v1, v0, v1
	v_lshlrev_b32_e32 v2, 3, v12
	s_waitcnt lgkmcnt(0)
	s_add_u32 s0, s40, 0x6000000
	v_ashrrev_i32_e32 v11, 6, v1
	v_and_b32_e32 v2, -16, v2
	s_addc_u32 s1, s41, 0
	v_add_u32_e32 v2, v11, v2
	s_add_u32 s3, s40, 0x1d100000
	v_and_b32_e32 v3, 3, v11
	v_lshrrev_b32_e32 v4, 2, v2
	v_lshlrev_b32_e32 v5, 1, v2
	v_and_b32_e32 v1, 0xc0, v1
	s_addc_u32 s8, s41, 0
	s_ashr_i32 s11, s10, 6
	v_and_or_b32 v3, v2, s12, v3
	v_and_b32_e32 v4, 4, v4
	v_and_b32_e32 v5, 24, v5
	v_sub_u32_e32 v0, v0, v1
	s_ashr_i32 s30, s10, 8
	s_lshl_b32 s9, s11, 10
	v_or3_b32 v3, v3, v4, v5
	v_lshlrev_b32_e32 v4, 5, v12
	v_ashrrev_i16_sdwa v0, v220, sext(v0) dst_sel:DWORD dst_unused:UNUSED_PAD src0_sel:DWORD src1_sel:BYTE_0
	v_readlane_b32 s12, v255, 6
	v_and_b32_e32 v4, 32, v4
	v_bfe_i32 v13, v0, 0, 16
	v_readlane_b32 s13, v255, 7
	s_add_u32 s60, s3, s12
	v_add_lshl_u32 v0, v4, v13, 1
	s_addc_u32 s61, s8, s13
	s_add_i32 s20, s9, 0
	v_lshl_add_u32 v188, v3, 10, v0
	s_add_i32 m0, s20, 0x10000
	v_lshl_add_u32 v202, v2, 10, v0
	global_load_lds_dwordx4 v188, s[60:61]
	s_add_i32 m0, s20, 0x12000
	s_add_u32 s12, s60, 0x20000
	global_load_lds_dwordx4 v198, s[60:61]
	s_addc_u32 s13, s61, 0
	s_add_i32 m0, s20, 0x14000
	v_mov_b32_e32 v199, v189
	global_load_lds_dwordx4 v188, s[12:13]
	s_add_i32 m0, s20, 0x16000
	v_mov_b32_e32 v203, v189
	global_load_lds_dwordx4 v198, s[12:13]
	v_readlane_b32 s12, v255, 29
	v_readlane_b32 s13, v255, 30
	s_add_u32 s58, s0, s12
	s_addc_u32 s59, s1, s13
	s_add_i32 s21, s20, 0x2000
	s_mov_b32 m0, s20
	s_add_u32 s12, s58, 0x20000
	global_load_lds_dwordx4 v202, s[58:59]
	s_mov_b32 m0, s21
	s_addc_u32 s13, s59, 0
	s_add_i32 s24, s20, 0x4000
	global_load_lds_dwordx4 v200, s[58:59]
	s_mov_b32 m0, s24
	s_add_i32 s29, s20, 0x6000
	global_load_lds_dwordx4 v202, s[12:13]
	s_mov_b32 m0, s29
	v_mov_b32_e32 v201, v189
	global_load_lds_dwordx4 v200, s[12:13]
	s_cmp_eq_u32 s30, 1
	v_lshl_add_u64 v[6:7], s[60:61], 0, v[188:189]
	v_lshl_add_u64 v[4:5], s[60:61], 0, v[198:199]
	v_lshl_add_u64 v[0:1], s[58:59], 0, v[202:203]
	s_cselect_b64 s[16:17], -1, 0
	s_cmp_lg_u32 s30, 1
	v_lshl_add_u64 v[2:3], s[58:59], 0, v[200:201]
	s_cbranch_scc1 .LBB0_564
	s_barrier
